# baseline (speedup 1.0000x reference)
; __device__ __forceinline__ int v_rd_base(int lane) { return ((lane & 3) << 3) | (((lane >> 2) & 3) << 6) | (((lane >> 4) & 1) << 5) | (((lane >> 5) & 1) << 8); }
; template <int MODE>
; __device__ __forceinline__ void attn_item(const Params& P, int b, int h, int qb, char* lds) {
;   int tid = threadIdx.x; asm volatile("" : "+v"(tid));
;   const int lane = tid & 63, wid = __builtin_amdgcn_readfirstlane(tid >> 6), r32 = lane & 31, hi = lane >> 5;
;   char* V_lds = lds;
;   char* K_lds = lds + 32768;
;   float* cs_l = (float*)(lds + 65536);
;   float* ws = (float*)(lds + 65536 + 512) + wid * 64;
;   float* al_l = ws; float* li_l = ws + 32;
;   const u16 *Qp, *Kp, *Vp;
;   if (MODE == 0) {
;     Qp = P_qA + (size_t)(b * 32 + h) * SEQ * 128; Kp = P_kA + (size_t)(b * 4 + (h >> 3)) * SEQ * 128; Vp = P_vA + (size_t)(b * 4 + (h >> 3)) * SEQ * 128;
;   } else {
;     Qp = P_q1 + (size_t)(b * 32 + h) * SEQ * 128; Kp = P_k1 + (size_t)(b * 32 + h) * SEQ * 128; Vp = P_v1 + (size_t)(b * 32 + h) * SEQ * 128;
;   }
;   const int q0 = qb * 256 + wid * 32, qpos = q0 + r32;
;   const int NT = 4 * qb + 4;
;   bf16x8 qr[8];
; #pragma unroll
;   for (int d0 = 0; d0 < 8; ++d0) qr[d0] = *(const bf16x8*)(Qp + (size_t)qpos * 128 + d0 * 16 + hi * 8);
;   const float* c2p = P_c2 + (size_t)(b * 32 + h) * SEQ;
;   float c2t = 0.f;
;   if (MODE == 1) c2t = c2p[qpos];
;   const u64* mrow = P_mask + (size_t)(b * SEQ + qpos) * 64;
;   const int kch = ((tid & 15) ^ ((tid >> 4) & 7)) * 8;
;   const size_t ksrc = (size_t)(tid >> 4) * 128 + kch;
;   const int kk4 = ((tid >> 7) & 1) * 8 + ((tid & 31) >> 2);
;   const int vk = ((kk4 & ~0xC) | ((kk4 & 4) << 1) | ((kk4 & 8) >> 1)) + ((tid >> 8) & 1) * 16;
;   const size_t vsrc = (size_t)vk * 128 + ((tid >> 5) & 3) * 32 + (tid & 3) * 8;
;   f32x4 stc = {0.f, 0.f, 0.f, 0.f}; u64 mw = 0;
;     ...
;   LOADT(NT - 1, 0);
;   float m_reg = 0.f;
;   int started = 0;
;   f32x16 o[4], ol;
; #pragma unroll
;   for (int d = 0; d < 4; ++d) o[d] = f32x16{};
;   ol = f32x16{};
;   const bf16x8 ones = {0x3F80, 0x3F80, 0x3F80, 0x3F80, 0x3F80, 0x3F80, 0x3F80, 0x3F80};
;   const int vb_lane = (int)(uintptr_t)V_lds + v_rd_base(lane);
.LBB0_681:
	s_bitcmp0_b32 s55, 0
	s_cselect_b32 s9, s51, s52
	s_lshl_b32 s0, s55, 1
	s_add_i32 s33, s53, s0
	v_mov_b32_e32 v12, v184
	s_add_i32 s0, s33, s54
	s_ashr_i32 s1, s0, 31
	v_readfirstlane_b32 s10, v12
	s_and_b32 s34, s10, 0x3fffffc0
	s_lshl_b64 s[0:1], s[0:1], 20
	s_add_u32 s0, s80, s0
	s_addc_u32 s1, s81, s1
	s_ashr_i32 s10, s10, 1
	s_lshl_b32 s35, s9, 8
	s_and_b32 s36, s10, 0xffffffe0
	v_and_b32_e32 v169, 31, v12
	s_add_i32 s56, s36, s35
	s_ashr_i32 s6, s33, 3
	v_or_b32_e32 v2, s56, v169
	s_add_i32 s6, s6, s50
	v_ashrrev_i32_e32 v3, 31, v2
	s_ashr_i32 s7, s6, 31
	v_lshlrev_b64 v[4:5], 8, v[2:3]
	s_lshl_b32 s57, s9, 2
	v_lshl_add_u64 v[4:5], s[0:1], 0, v[4:5]
	s_lshl_b64 s[10:11], s[6:7], 20
	v_readlane_b32 s0, v250, 32
	v_bfe_u32 v13, v12, 5, 1
	s_add_u32 s0, s0, s10
	v_readlane_b32 s1, v250, 33
	v_lshrrev_b32_e32 v7, 5, v12
	v_lshlrev_b32_e32 v0, 4, v13
	s_addc_u32 s1, s1, s11
	v_and_b32_e32 v8, 4, v7
	v_lshrrev_b32_e32 v7, 1, v12
	v_lshl_add_u64 v[4:5], v[4:5], 0, v[0:1]
	s_add_u32 s6, s86, s10
	v_and_b32_e32 v10, 8, v7
	v_lshrrev_b32_e32 v11, 4, v12
	global_load_dwordx4 v[156:159], v[4:5], off
	global_load_dwordx4 v[152:155], v[4:5], off offset:32
	global_load_dwordx4 v[148:151], v[4:5], off offset:64
	global_load_dwordx4 v[144:147], v[4:5], off offset:96
	global_load_dwordx4 v[140:143], v[4:5], off offset:128
	global_load_dwordx4 v[136:139], v[4:5], off offset:160
	global_load_dwordx4 v[132:135], v[4:5], off offset:192
	global_load_dwordx4 v[128:131], v[4:5], off offset:224
	s_addc_u32 s7, s87, s11
	v_and_b32_e32 v5, 15, v12
	v_ashrrev_i32_e32 v4, 4, v12
	v_bfe_u32 v9, v12, 2, 2
	s_or_b32 s58, s57, 3
	v_and_or_b32 v10, v11, 16, v10
	v_bitop3_b32 v6, v4, v5, 7 bitop3:0x6c
	v_ashrrev_i32_e32 v5, 31, v4
	v_lshlrev_b32_e32 v15, 3, v12
	s_lshl_b32 s16, s58, 14
	v_or3_b32 v8, v8, v9, v10
	v_and_b32_e32 v14, 0x60, v12
	v_and_b32_e32 v16, 24, v15
	s_add_u32 s0, s0, s16
	v_lshlrev_b64 v[4:5], 8, v[4:5]
	v_lshlrev_b32_e32 v17, 4, v6
	v_lshlrev_b32_e32 v8, 7, v8
	s_addc_u32 s1, s1, 0
	v_or_b32_e32 v6, v4, v17
	v_mov_b32_e32 v7, v5
	v_or3_b32 v8, v8, v14, v16
	v_lshlrev_b32_e32 v14, 4, v12
	v_lshl_add_u64 v[6:7], s[0:1], 0, v[6:7]
	s_add_u32 s0, s6, s16
	v_add_u32_e32 v180, 16, v14
	s_addc_u32 s1, s7, 0
	v_lshlrev_b32_e32 v8, 1, v8
	v_mov_b32_e32 v9, v1
	v_add_u32_e32 v16, 0x8000, v180
	v_lshl_add_u64 v[10:11], s[0:1], 0, v[8:9]
	v_readfirstlane_b32 s0, v16
	s_mov_b32 m0, s0
	v_readfirstlane_b32 s0, v180
	v_add_u32_e32 v16, 0xa000, v180
	global_load_lds_dwordx4 v[6:7], off
	s_mov_b32 m0, s0
	v_readfirstlane_b32 s0, v16
	global_load_lds_dwordx4 v[10:11], off
	v_lshl_add_u64 v[6:7], v[6:7], 0, s[18:19]
	s_mov_b32 m0, s0
	v_add_u32_e32 v2, s49, v2
	global_load_lds_dwordx4 v[6:7], off
	v_lshl_add_u64 v[6:7], v[10:11], 0, s[18:19]
	v_add_u32_e32 v10, 0x2000, v180
	v_ashrrev_i32_e32 v3, 31, v2
	v_readfirstlane_b32 s0, v10
	s_mov_b32 m0, s0
	v_readlane_b32 s0, v250, 42
	v_lshlrev_b64 v[2:3], 9, v[2:3]
	v_readlane_b32 s1, v250, 43
	s_lshl_b32 s16, s9, 5
	global_load_lds_dwordx4 v[6:7], off
	v_lshl_add_u64 v[2:3], s[0:1], 0, v[2:3]
	v_lshl_add_u64 v[2:3], v[2:3], 0, s[16:17]
	global_load_dwordx2 v[166:167], v[2:3], off offset:24
	s_lshl_b32 s0, s34, 2
	s_add_i32 s0, s0, 16
	s_add_i32 s0, s0, 0x10200
	v_lshlrev_b32_e32 v6, 1, v12
	s_or_b32 s60, s56, 31
	v_and_b32_e32 v6, 32, v6
	s_cmp_lg_u32 16, -1
	v_and_b32_e32 v3, 0xc0, v14
	v_and_or_b32 v6, v15, s40, v6
	v_lshl_add_u32 v173, v169, 2, s0
	v_add_u32_e32 v172, s0, v0
	s_cselect_b32 s0, 16, 0
	v_add3_u32 v171, v3, s0, v6
	s_add_i32 s0, s49, s35
	v_and_b32_e32 v2, 63, v12
	s_add_i32 s0, s0, s36
	v_cmp_gt_u32_e64 s[6:7], 32, v2
	v_add_u32_e32 v2, s0, v169
	v_ashrrev_i32_e32 v3, 31, v2
	s_lshl_b32 s0, s9, 16
	v_lshlrev_b64 v[2:3], 9, v[2:3]
	s_or_b32 s10, s10, s0
	v_and_b32_e32 v7, 0x70, v14
	v_bitop3_b32 v183, v0, v14, s41 bitop3:0x78
	v_or_b32_e32 v2, s16, v2
	s_waitcnt vmcnt(0)
	v_lshl_add_u64 v[162:163], s[10:11], 0, v[4:5]
	v_mov_b32_e32 v14, v1
	v_mov_b32_e32 v15, v1
	v_lshlrev_b32_e32 v170, 2, v13
	v_bitop3_b32 v181, v0, v7, 32 bitop3:0x36
	v_bitop3_b32 v179, v0, v7, 64 bitop3:0x36
	v_bitop3_b32 v178, v0, v7, s2 bitop3:0x36
	v_bitop3_b32 v177, v0, v7, s42 bitop3:0x36
	v_bitop3_b32 v176, v0, v7, s43 bitop3:0x36
	v_bitop3_b32 v175, v0, v7, s3 bitop3:0x36
	v_bitop3_b32 v174, v0, v7, s44 bitop3:0x36
	v_lshl_add_u64 v[160:161], v[2:3], 0, s[20:21]
	v_or_b32_e32 v162, v162, v17
	v_lshl_add_u64 v[164:165], s[10:11], 0, v[8:9]
	v_mov_b32_e32 v0, v1
	v_mov_b32_e32 v2, v1
	v_mov_b32_e32 v3, v1
	v_mov_b32_e32 v4, v1
	v_mov_b32_e32 v5, v1
	v_mov_b32_e32 v6, v1
	v_mov_b32_e32 v7, v1
	v_mov_b32_e32 v8, v1
	v_mov_b32_e32 v10, v1
	v_mov_b32_e32 v11, v1
	v_mov_b32_e32 v12, v1
	v_mov_b32_e32 v13, v1
	v_mov_b64_e32 v[30:31], v[14:15]
	v_mov_b64_e32 v[46:47], v[14:15]
	v_mov_b64_e32 v[62:63], v[14:15]
	v_mov_b64_e32 v[78:79], v[14:15]
	v_mov_b64_e32 v[94:95], v[14:15]
	s_mov_b32 s59, 0
	v_lshl_add_u32 v182, v169, 8, 16
	s_or_b32 s16, s35, 0xc0
	v_mov_b32_e32 v186, 0
	v_mov_b64_e32 v[28:29], v[12:13]
	v_mov_b64_e32 v[26:27], v[10:11]
	v_mov_b64_e32 v[24:25], v[8:9]
	v_mov_b64_e32 v[22:23], v[6:7]
	v_mov_b64_e32 v[20:21], v[4:5]
	v_mov_b64_e32 v[18:19], v[2:3]
	v_mov_b64_e32 v[16:17], v[0:1]
	v_mov_b64_e32 v[44:45], v[12:13]
	v_mov_b64_e32 v[42:43], v[10:11]
	v_mov_b64_e32 v[40:41], v[8:9]
	v_mov_b64_e32 v[38:39], v[6:7]
	v_mov_b64_e32 v[36:37], v[4:5]
	v_mov_b64_e32 v[34:35], v[2:3]
	v_mov_b64_e32 v[32:33], v[0:1]
	v_mov_b64_e32 v[60:61], v[12:13]
	v_mov_b64_e32 v[58:59], v[10:11]
	v_mov_b64_e32 v[56:57], v[8:9]
	v_mov_b64_e32 v[54:55], v[6:7]
	v_mov_b64_e32 v[52:53], v[4:5]
	v_mov_b64_e32 v[50:51], v[2:3]
	v_mov_b64_e32 v[48:49], v[0:1]
	v_mov_b64_e32 v[76:77], v[12:13]
	v_mov_b64_e32 v[74:75], v[10:11]
	v_mov_b64_e32 v[72:73], v[8:9]
	v_mov_b64_e32 v[70:71], v[6:7]
	v_mov_b64_e32 v[68:69], v[4:5]
	v_mov_b64_e32 v[66:67], v[2:3]
	v_mov_b64_e32 v[64:65], v[0:1]
	s_mov_b32 s0, 0
	v_mov_b64_e32 v[92:93], v[12:13]
	v_mov_b64_e32 v[90:91], v[10:11]
	v_mov_b64_e32 v[88:89], v[8:9]
	v_mov_b64_e32 v[86:87], v[6:7]
	v_mov_b64_e32 v[84:85], v[4:5]
	v_mov_b64_e32 v[82:83], v[2:3]
	v_mov_b64_e32 v[80:81], v[0:1]
	v_lshl_add_u64 v[162:163], v[162:163], 0, s[94:95]
	v_lshl_add_u64 v[164:165], v[164:165], 0, s[94:95]
	v_lshl_add_u64 v[160:161], v[160:161], 0, s[94:95]
	v_lshl_add_u64 v[248:249], v[162:163], 0, s[26:27]
	v_lshl_add_u64 v[252:253], v[164:165], 0, s[28:29]
	v_lshl_add_u64 v[162:163], v[162:163], 0, s[22:23]
	v_lshl_add_u64 v[164:165], v[164:165], 0, s[24:25]
	v_readfirstlane_b32 s99, v180
; template <int MODE>
; __device__ __forceinline__ void attn_item(const Params& P, int b, int h, int qb, char* lds) {
;     ...
;   for (int it = 0; it < NT; ++it) {
;     const int t = NT - 1 - it, buf = it & 1;
;     asm volatile("s_waitcnt vmcnt(0)" ::: "memory");
;     const u64 mcur = mw;
;     if (MODE == 1) { if (tid < 16) *(f32x4*)(cs_l + buf * 64 + tid * 4) = stc; }
;     __syncthreads();
;     if (it + 1 < NT) LOADT(t - 1, buf ^ 1);
;     const int kb = t * 64;
;     if (kb <= q0 + 31) {
.LBB0_682:
	s_and_b32 s9, s59, 0x4000
	s_xor_b32 s1, s9, 0x4000
	s_add_u32 s1, s99, s1
	s_waitcnt vmcnt(0)
	s_waitcnt lgkmcnt(0)
	s_barrier
	s_add_u32 m0, s1, 0x8000
	s_nop 0
	global_load_lds_dwordx4 v[162:163], off
	s_mov_b32 m0, s1
	s_nop 0
	global_load_lds_dwordx4 v[164:165], off
	s_add_u32 m0, s1, 0xa000
	s_nop 0
	global_load_lds_dwordx4 v[248:249], off
	s_add_u32 m0, s1, 0x2000
	s_cmp_gt_i32 s16, s60
	global_load_lds_dwordx4 v[252:253], off
	global_load_dwordx2 v[14:15], v[160:161], off
	s_cbranch_scc1 .LBB0_699
	s_cmp_lt_u32 s98, 4
	s_cbranch_scc1 .Lmy_pr_a
	s_setprio 1

; __device__ __forceinline__ int v_rd_base(int lane) { return ((lane & 3) << 3) | (((lane >> 2) & 3) << 6) | (((lane >> 4) & 1) << 5) | (((lane >> 5) & 1) << 8); }
; template <int MODE>
; __device__ __forceinline__ void attn_item(const Params& P, int b, int h, int qb, char* lds) {
;     ...
;   LOADT(NT - 1, 0);
;   float m_reg = 0.f;
;   int started = 0;
;   f32x16 o[4], ol;
; #pragma unroll
;   for (int d = 0; d < 4; ++d) o[d] = f32x16{};
;   ol = f32x16{};
;   const bf16x8 ones = {0x3F80, 0x3F80, 0x3F80, 0x3F80, 0x3F80, 0x3F80, 0x3F80, 0x3F80};
;   const int vb_lane = (int)(uintptr_t)V_lds + v_rd_base(lane);
;   for (int it = 0; it < NT; ++it) {
;     const int t = NT - 1 - it, buf = it & 1;
;     asm volatile("s_waitcnt vmcnt(0)" ::: "memory");
;     const u64 mcur = mw;
;     if (MODE == 1) { if (tid < 16) *(f32x4*)(cs_l + buf * 64 + tid * 4) = stc; }
;     __syncthreads();
;     if (it + 1 < NT) LOADT(t - 1, buf ^ 1);
.LBB0_699:
	s_sub_i32 s16, s16, 64
	s_addk_i32 s59, 0x4000
	v_lshl_add_u64 v[160:161], v[160:161], 0, -8
	v_lshl_add_u64 v[162:163], v[162:163], 0, s[30:31]
	s_cmp_eq_u32 s16, 0
	v_lshl_add_u64 v[164:165], v[164:165], 0, s[30:31]
	v_lshl_add_u64 v[248:249], v[248:249], 0, s[30:31]
	v_lshl_add_u64 v[252:253], v[252:253], 0, s[30:31]
	s_cbranch_scc1 .LBB0_702
	s_waitcnt vmcnt(0)
	v_mov_b64_e32 v[166:167], v[14:15]
	s_branch .LBB0_682
